# Hyena conv taps (phase 4): the six rows read per batch pair are touched together at the top of the trip so the serial reads hit in cache
# baseline (speedup 1.0000x reference)
; DEV float bf2f(unsigned short h) { return __uint_as_float(((unsigned)h) << 16); }
; DEV void hy_conv8(const bf16_t* ht, const int b, const int c, const int L, const int t0, const bool act_, const float* cwp, const float* cbp, float (&x0o)[8], float (&wo)[8]) {
;     float outv[3][8];
; #pragma unroll
;     for (int q = 0; q < 3; ++q) { const int cp = q * 512 + c; const bf16_t* src = ht + (size_t)(b * 1536 + cp) * L;
;         const float w0 = cwp[cp], w1 = cwp[1536 + cp], w2 = cwp[3072 + cp], bq = cbp[cp];
;         float x[10];
;         if (act_) { const u32x4 raw = *(const u32x4*)(src + t0);
;             x[1] = __uint_as_float(raw.x << 16); x[2] = __uint_as_float(raw.x & 0xffff0000u); x[3] = __uint_as_float(raw.y << 16); x[4] = __uint_as_float(raw.y & 0xffff0000u);
;             x[5] = __uint_as_float(raw.z << 16); x[6] = __uint_as_float(raw.z & 0xffff0000u); x[7] = __uint_as_float(raw.w << 16); x[8] = __uint_as_float(raw.w & 0xffff0000u);
;             x[0] = (t0 > 0) ? bf2f(src[t0 - 1]) : 0.f; x[9] = (t0 + 8 < L) ? bf2f(src[t0 + 8]) : 0.f; }
; template <int LO, int HI>
; DEV void run_phases(LAS unsigned char* lds, const int ph_lo, const int ph_hi, const int G, const int wave0, unsigned& nbar) {
;     ...
;                 for (int bp0 = 0; bp0 < 4; bp0 += npb) { const int bp = bp0 + (act_ ? pl : 0);
;                     float xk[2][8], wk[2][8];
;                     hy_conv8(ht, 2 * bp, c, L, t0, act_, cwp, cbp, xk[0], wk[0]); hy_conv8(ht, 2 * bp + 1, c, L, t0, act_, cwp, cbp, xk[1], wk[1]);
.LBB0_900:
	v_readlane_b32 s12, v248, 8
	v_readlane_b32 s13, v248, 9
	global_load_dword v78, v1, s[24:25]
	v_add_u32_e32 v79, s88, v75
	v_mov_b32_e32 v87, 0
	v_mov_b32_e32 v92, 0
	v_mov_b32_e32 v91, 0
	global_load_dword v82, v1, s[12:13]
	v_readlane_b32 s12, v249, 21
	v_readlane_b32 s13, v249, 22
	s_nop 4
	global_load_dword v80, v1, s[12:13]
	global_load_dword v81, v1, s[30:31]
	s_movk_i32 s12, 0xc00
	v_mul_lo_u32 v15, v79, s12
	v_mov_b32_e32 v90, 0
	v_mov_b32_e32 v89, 0
	v_mov_b32_e32 v88, 0
	v_mov_b32_e32 v86, 0
	v_mov_b32_e32 v84, 0
	v_mov_b32_e32 v85, 0
	v_mov_b32_e32 v83, 0
	s_and_saveexec_b64 s[16:17], s[6:7]
	v_readlane_b32 s12, v248, 6
	s_nop 0
	v_add_u32_e32 v204, s12, v15
	v_ashrrev_i32_e32 v205, 31, v204
	v_lshlrev_b64 v[204:205], s91, v[204:205]
	v_lshl_add_u64 v[204:205], v[204:205], 1, v[42:43]
	global_load_dword v206, v[204:205], off
	v_readlane_b32 s12, v249, 62
	s_nop 0
	v_add_u32_e32 v204, s12, v15
	v_ashrrev_i32_e32 v205, 31, v204
	v_lshlrev_b64 v[204:205], s91, v[204:205]
	v_lshl_add_u64 v[204:205], v[204:205], 1, v[42:43]
	global_load_dword v206, v[204:205], off
	v_readlane_b32 s12, v249, 47
	s_nop 0
	v_add_u32_e32 v204, s12, v15
	v_ashrrev_i32_e32 v205, 31, v204
	v_lshlrev_b64 v[204:205], s91, v[204:205]
	v_lshl_add_u64 v[204:205], v[204:205], 1, v[42:43]
	global_load_dword v206, v[204:205], off
	v_readlane_b32 s12, v248, 6
	s_nop 0
	v_add_u32_e32 v204, s12, v15
	v_add_u32_e32 v204, 0x600, v204
	v_ashrrev_i32_e32 v205, 31, v204
	v_lshlrev_b64 v[204:205], s91, v[204:205]
	v_lshl_add_u64 v[204:205], v[204:205], 1, v[42:43]
	global_load_dword v206, v[204:205], off
	v_readlane_b32 s12, v249, 62
	s_nop 0
	v_add_u32_e32 v204, s12, v15
	v_add_u32_e32 v204, 0x600, v204
	v_ashrrev_i32_e32 v205, 31, v204
	v_lshlrev_b64 v[204:205], s91, v[204:205]
	v_lshl_add_u64 v[204:205], v[204:205], 1, v[42:43]
	global_load_dword v206, v[204:205], off
	v_readlane_b32 s12, v249, 47
	s_nop 0
	v_add_u32_e32 v204, s12, v15
	v_add_u32_e32 v204, 0x600, v204
	v_ashrrev_i32_e32 v205, 31, v204
	v_lshlrev_b64 v[204:205], s91, v[204:205]
	v_lshl_add_u64 v[204:205], v[204:205], 1, v[42:43]
	global_load_dword v206, v[204:205], off
	s_or_b64 exec, exec, s[16:17]
	s_and_saveexec_b64 s[14:15], s[6:7]
	s_cbranch_execz .LBB0_906
	v_readlane_b32 s12, v248, 6
	v_mov_b32_e32 v87, 0
	v_mov_b32_e32 v83, 0
	v_add_u32_e32 v2, s12, v15
	v_ashrrev_i32_e32 v3, 31, v2
	v_lshlrev_b64 v[2:3], s91, v[2:3]
	v_lshl_add_u64 v[6:7], v[2:3], 1, v[42:43]
	global_load_dwordx4 v[2:5], v[6:7], off
	v_readlane_b32 s13, v248, 7
	s_and_saveexec_b64 s[16:17], s[8:9]
	s_cbranch_execz .LBB0_903
	global_load_ushort v0, v[6:7], off offset:-2
	s_waitcnt vmcnt(0)
	v_lshlrev_b32_e32 v83, 16, v0
